# B1 pool item: projection weight fragments, gate and scale loads hoisted before the barrier (one round trip instead of seven)
# speedup vs baseline: 1.0134x; 1.0134x over previous
.LBB0_362:
	s_or_b64 exec, exec, s[0:1]
	v_ashrrev_i32_e32 v29, 7, v0
	v_add_u32_e32 v2, s72, v29
	v_ashrrev_i32_e32 v3, 31, v2
	v_lshrrev_b32_e32 v1, 1, v0
	v_and_b32_e32 v17, 31, v0
	v_lshlrev_b64 v[2:3], 6, v[2:3]
	v_and_b32_e32 v30, 32, v1
	v_or3_b32 v2, v2, v30, v17
	v_readlane_b32 s0, v215, 57
	v_bfe_u32 v28, v0, 5, 1
	v_lshlrev_b64 v[2:3], 7, v[2:3]
	v_readlane_b32 s1, v215, 58
	v_lshlrev_b32_e32 v64, 4, v28
	v_mad_u32_u24 v1, v17, s26, 0
	v_lshl_add_u64 v[2:3], s[0:1], 0, v[2:3]
	v_lshl_add_u64 v[26:27], v[2:3], 0, v[64:65]
	v_and_b32_e32 v0, 0xffffff80, v0
	global_load_dwordx4 v[82:85], v[26:27], off
	global_load_dwordx4 v[86:89], v[26:27], off offset:32
	global_load_dwordx4 v[90:93], v[26:27], off offset:64
	global_load_dwordx4 v[94:97], v[26:27], off offset:96
	v_or_b32_e32 v146, v17, v16
	v_lshlrev_b32_e32 v147, 6, v29
	v_lshl_or_b32 v147, v28, 2, v147
	v_or_b32_e32 v147, v147, v30
	v_readlane_b32 s0, v214, 12
	v_readlane_b32 s1, v214, 13
	v_mul_lo_u32 v148, v146, s83
	v_lshl_add_u32 v148, v147, 1, v148
	v_lshlrev_b32_e32 v149, 2, v147
	s_nop 3
	global_load_dwordx2 v[138:139], v148, s[0:1] offset:512
	global_load_dwordx2 v[140:141], v148, s[0:1] offset:528
	global_load_dwordx2 v[142:143], v148, s[0:1] offset:544
	global_load_dwordx2 v[144:145], v148, s[0:1] offset:560
	global_load_dwordx4 v[114:117], v149, s[50:51]
	global_load_dwordx4 v[118:121], v149, s[50:51] offset:32
	global_load_dwordx4 v[122:125], v149, s[50:51] offset:64
	global_load_dwordx4 v[150:153], v149, s[50:51] offset:96
	s_waitcnt lgkmcnt(0)
	s_barrier
	v_add3_u32 v31, v1, v0, v64
	s_nop 0
	ds_read_b128 v[4:7], v31 offset:48128
	ds_read_b128 v[18:21], v31 offset:48160
	s_nop 0
	v_or_b32_e32 v64, v17, v16
	v_lshlrev_b32_e32 v16, 6, v29
	v_lshlrev_b32_e32 v17, 2, v28
	v_readlane_b32 s0, v214, 12
	v_readlane_b32 s1, v214, 13
	s_waitcnt vmcnt(11) lgkmcnt(1)
	v_mfma_f32_32x32x16_bf16 v[0:15], v[82:85], v[4:7], 0
	s_waitcnt vmcnt(10) lgkmcnt(0)
	v_mfma_f32_32x32x16_bf16 v[0:15], v[86:89], v[18:21], v[0:15]
	s_nop 0
	ds_read_b128 v[22:25], v31 offset:48192
	s_waitcnt vmcnt(9) lgkmcnt(0)
	v_mfma_f32_32x32x16_bf16 v[0:15], v[90:93], v[22:25], v[0:15]
	s_nop 0
	ds_read_b128 v[22:25], v31 offset:48224
	s_waitcnt vmcnt(8) lgkmcnt(0)
	v_mfma_f32_32x32x16_bf16 v[0:15], v[94:97], v[22:25], v[0:15]
	v_or3_b32 v18, v17, v16, v30
	v_mov_b64_e32 v[16:17], s[0:1]
	v_ashrrev_i32_e32 v19, 31, v18
	v_mad_u64_u32 v[26:27], s[0:1], v64, s83, v[16:17]
	v_lshlrev_b64 v[28:29], 1, v[18:19]
	v_lshl_add_u64 v[20:21], v[18:19], 2, s[50:51]
	v_lshl_add_u64 v[18:19], v[26:27], 0, v[28:29]
	s_nop 0
	s_nop 0
	s_nop 2
	v_mov_b32_e32 v36, v0
	v_readlane_b32 s0, v214, 4
	v_lshlrev_b64 v[16:17], 11, v[64:65]
	v_readlane_b32 s1, v214, 5
	s_waitcnt vmcnt(0)
	v_mov_b32_e32 v26, v138
	v_mov_b32_e32 v27, v139
	v_lshlrev_b32_e32 v31, 16, v26
	v_and_b32_e32 v33, 0xffff0000, v26
	v_mul_f32_e32 v26, 0xbfb8aa3b, v31
	v_exp_f32_e32 v26, v26
	v_mul_f32_e32 v0, 0xbfb8aa3b, v33
	v_exp_f32_e32 v0, v0
	v_mov_b32_e32 v22, v114
	v_mov_b32_e32 v23, v115
	v_mov_b32_e32 v24, v116
	v_mov_b32_e32 v25, v117
	v_mov_b32_e32 v30, v22
	v_add_f32_e32 v26, 1.0, v26
	v_rcp_f32_e32 v37, v26
	v_add_f32_e32 v0, 1.0, v0
	v_mov_b32_e32 v32, v23
	v_lshlrev_b32_e32 v35, 16, v27
	v_pk_mul_f32 v[30:31], v[36:37], v[30:31]
	v_and_b32_e32 v27, 0xffff0000, v27
	v_mul_f32_e32 v22, v30, v31
	v_rcp_f32_e32 v31, v0
	v_mov_b32_e32 v30, v1
	v_mov_b32_e32 v34, v24
	v_lshl_add_u64 v[16:17], s[0:1], 0, v[16:17]
	v_pk_mul_f32 v[0:1], v[30:31], v[32:33]
	v_mov_b32_e32 v26, v25
	v_mul_f32_e32 v0, v0, v1
	v_mul_f32_e32 v1, 0xbfb8aa3b, v35
	v_exp_f32_e32 v1, v1
	v_cvt_pk_bf16_f32 v0, v22, v0
	v_mov_b32_e32 v22, v2
	v_mul_f32_e32 v2, 0xbfb8aa3b, v27
	v_add_f32_e32 v1, 1.0, v1
	v_rcp_f32_e32 v23, v1
	v_exp_f32_e32 v2, v2
	v_lshl_add_u64 v[16:17], v[16:17], 0, v[28:29]
	v_mov_b32_e32 v30, v4
	v_pk_mul_f32 v[22:23], v[22:23], v[34:35]
	v_add_f32_e32 v2, 1.0, v2
	v_mul_f32_e32 v1, v22, v23
	v_rcp_f32_e32 v23, v2
	v_mov_b32_e32 v22, v3
	v_pk_mul_f32 v[2:3], v[22:23], v[26:27]
	s_nop 0
	v_mul_f32_e32 v2, v2, v3
	v_cvt_pk_bf16_f32 v1, v1, v2
	global_store_dwordx2 v[16:17], v[0:1], off
	v_mov_b32_e32 v0, v118
	v_mov_b32_e32 v1, v119
	v_mov_b32_e32 v2, v120
	v_mov_b32_e32 v3, v121
	v_mov_b32_e32 v22, v140
	v_mov_b32_e32 v23, v141
	v_mov_b32_e32 v24, v0
	v_lshlrev_b32_e32 v25, 16, v22
	v_and_b32_e32 v27, 0xffff0000, v22
	v_mul_f32_e32 v22, 0xbfb8aa3b, v25
	v_exp_f32_e32 v22, v22
	v_mul_f32_e32 v0, 0xbfb8aa3b, v27
	v_exp_f32_e32 v0, v0
	v_mov_b32_e32 v26, v1
	v_add_f32_e32 v22, 1.0, v22
	v_rcp_f32_e32 v31, v22
	v_add_f32_e32 v0, 1.0, v0
	v_lshlrev_b32_e32 v29, 16, v23
	v_and_b32_e32 v23, 0xffff0000, v23
	v_pk_mul_f32 v[24:25], v[30:31], v[24:25]
	v_mov_b32_e32 v28, v2
	v_mul_f32_e32 v4, v24, v25
	v_rcp_f32_e32 v25, v0
	v_mov_b32_e32 v24, v5
	v_mul_f32_e32 v2, 0xbfb8aa3b, v23
	v_exp_f32_e32 v2, v2
	v_pk_mul_f32 v[0:1], v[24:25], v[26:27]
	v_mov_b32_e32 v22, v3
	v_mul_f32_e32 v0, v0, v1
	v_mul_f32_e32 v1, 0xbfb8aa3b, v29
	v_exp_f32_e32 v1, v1
	v_cvt_pk_bf16_f32 v0, v4, v0
	v_mov_b32_e32 v4, v6
	v_add_f32_e32 v2, 1.0, v2
	v_add_f32_e32 v1, 1.0, v1
	v_rcp_f32_e32 v5, v1
	v_mov_b32_e32 v26, v8
	v_pk_mul_f32 v[4:5], v[4:5], v[28:29]
	s_nop 0
	v_mul_f32_e32 v1, v4, v5
	v_rcp_f32_e32 v5, v2
	v_mov_b32_e32 v4, v7
	v_pk_mul_f32 v[2:3], v[4:5], v[22:23]
	s_nop 0
	v_mul_f32_e32 v2, v2, v3
	v_cvt_pk_bf16_f32 v1, v1, v2
	global_store_dwordx2 v[16:17], v[0:1], off offset:16
	v_mov_b32_e32 v0, v122
	v_mov_b32_e32 v1, v123
	v_mov_b32_e32 v2, v124
	v_mov_b32_e32 v3, v125
	v_mov_b32_e32 v4, v142
	v_mov_b32_e32 v5, v143
	v_mov_b32_e32 v6, v0
	v_lshlrev_b32_e32 v7, 16, v4
	v_and_b32_e32 v23, 0xffff0000, v4
	v_mul_f32_e32 v4, 0xbfb8aa3b, v7
	v_exp_f32_e32 v4, v4
	v_mul_f32_e32 v0, 0xbfb8aa3b, v23
	v_exp_f32_e32 v0, v0
	v_mov_b32_e32 v22, v1
	v_add_f32_e32 v4, 1.0, v4
	v_rcp_f32_e32 v27, v4
	v_add_f32_e32 v0, 1.0, v0
	v_lshlrev_b32_e32 v25, 16, v5
	v_and_b32_e32 v5, 0xffff0000, v5
	v_pk_mul_f32 v[6:7], v[26:27], v[6:7]
	v_mov_b32_e32 v24, v2
	v_mul_f32_e32 v4, v6, v7
	v_rcp_f32_e32 v7, v0
	v_mov_b32_e32 v6, v9
	v_mul_f32_e32 v2, 0xbfb8aa3b, v5
	v_exp_f32_e32 v2, v2
	v_pk_mul_f32 v[0:1], v[6:7], v[22:23]
	v_mov_b32_e32 v6, v10
	v_mul_f32_e32 v0, v0, v1
	v_mul_f32_e32 v1, 0xbfb8aa3b, v25
	v_exp_f32_e32 v1, v1
	v_add_f32_e32 v2, 1.0, v2
	v_cvt_pk_bf16_f32 v0, v4, v0
	v_mov_b32_e32 v4, v3
	v_add_f32_e32 v1, 1.0, v1
	v_rcp_f32_e32 v7, v1
	s_nop 0
	v_pk_mul_f32 v[6:7], v[6:7], v[24:25]
	s_nop 0
	v_mul_f32_e32 v1, v6, v7
	v_rcp_f32_e32 v7, v2
	v_mov_b32_e32 v6, v11
	v_pk_mul_f32 v[2:3], v[6:7], v[4:5]
	s_nop 0
	v_mul_f32_e32 v2, v2, v3
	v_cvt_pk_bf16_f32 v1, v1, v2
	global_store_dwordx2 v[16:17], v[0:1], off offset:32
	v_mov_b32_e32 v0, v150
	v_mov_b32_e32 v1, v151
	v_mov_b32_e32 v2, v152
	v_mov_b32_e32 v3, v153
	v_mov_b32_e32 v4, v144
	v_mov_b32_e32 v5, v145
	v_mov_b32_e32 v18, v12
	v_mov_b32_e32 v6, v0
	v_lshlrev_b32_e32 v7, 16, v4
	v_and_b32_e32 v9, 0xffff0000, v4
	v_mul_f32_e32 v4, 0xbfb8aa3b, v7
	v_exp_f32_e32 v4, v4
	v_mul_f32_e32 v0, 0xbfb8aa3b, v9
	v_exp_f32_e32 v0, v0
	v_mov_b32_e32 v8, v1
	v_add_f32_e32 v4, 1.0, v4
	v_rcp_f32_e32 v19, v4
	v_add_f32_e32 v0, 1.0, v0
	v_lshlrev_b32_e32 v11, 16, v5
	v_and_b32_e32 v5, 0xffff0000, v5
	v_pk_mul_f32 v[6:7], v[18:19], v[6:7]
	v_mov_b32_e32 v10, v2
	v_mul_f32_e32 v4, v6, v7
	v_rcp_f32_e32 v7, v0
	v_mov_b32_e32 v6, v13
	v_mul_f32_e32 v2, 0xbfb8aa3b, v5
	v_exp_f32_e32 v2, v2
	v_pk_mul_f32 v[0:1], v[6:7], v[8:9]
	v_mov_b32_e32 v6, v14
	v_mul_f32_e32 v0, v0, v1
	v_mul_f32_e32 v1, 0xbfb8aa3b, v11
	v_exp_f32_e32 v1, v1
	v_add_f32_e32 v2, 1.0, v2
	v_cvt_pk_bf16_f32 v0, v4, v0
	v_mov_b32_e32 v4, v3
	v_add_f32_e32 v1, 1.0, v1
	v_rcp_f32_e32 v7, v1
	s_nop 0
	v_pk_mul_f32 v[6:7], v[6:7], v[10:11]
	s_nop 0
	v_mul_f32_e32 v1, v6, v7
	v_rcp_f32_e32 v7, v2
	v_mov_b32_e32 v6, v15
	v_pk_mul_f32 v[2:3], v[6:7], v[4:5]
	s_nop 0
	v_mul_f32_e32 v2, v2, v3
	v_cvt_pk_bf16_f32 v1, v1, v2
	global_store_dwordx2 v[16:17], v[0:1], off offset:48
